# norm phases: lane^16 and lane^32 reduction steps as permlane16/32 swaps instead of LDS shuffles
# baseline (speedup 1.0000x reference)
; DI unsigned pk2(float lo, float hi) { f32x2 v = {lo, hi}; bf16x2_t b = __builtin_convertvector(v, bf16x2_t); return __builtin_bit_cast(unsigned, b); }
; DI void norm_row16_finish(int m, const f32x4 (&v)[4], float s, const float* gain, const float* mod, int shofs, int scofs, bf16_t* XN, int lane) {
;     const float* mb = mod + (size_t)row_batch(m) * NMOD;
;     const float inv = __builtin_amdgcn_rsqf(s * (1.f / D) + EPS);
; #pragma unroll
;     for (int j = 0; j < 2; ++j) {
;         const int c = 8 * (64 * j + lane);
;         u32x4 w;
; #pragma unroll
;         for (int q = 0; q < 2; ++q) {
;             const f32x4 g4 = *(const f32x4*)(gain + c + 4 * q), sc4 = *(const f32x4*)(mb + scofs + c + 4 * q), sh4 = *(const f32x4*)(mb + shofs + c + 4 * q);
;             const f32x4 o = v[2 * j + q] * inv * g4 * (sc4 + 1.f) + sh4;
;             if (q == 0) { w.x = pk2(o[0], o[1]); w.y = pk2(o[2], o[3]); } else { w.z = pk2(o[0], o[1]); w.w = pk2(o[2], o[3]); }
;         }
;         *(u32x4*)(XN + (size_t)m * D + c) = w;
;     }
; DI void norm_phase_b16(const bf16_t* src, const float* gain, const float* mod, int shofs, int scofs, bf16_t* XN, int wave, int lane) {
;     ...
;     for (int m = gw; m < M; m += 2 * NGW) {
;         const int m2 = m + NGW; const bool two = m2 < M; const int mb2 = two ? m2 : m;
;         f32x4 va[4], vb[4]; float sa = 0.f, sb = 0.f;
; #pragma unroll
;         for (int j = 0; j < 2; ++j) {
;             const u32x4 a = *(const u32x4*)(src + (size_t)m * D + 8 * (64 * j + lane)), b = *(const u32x4*)(src + (size_t)mb2 * D + 8 * (64 * j + lane));
;             u32x2 t; t.x = a.x; t.y = a.y; va[2 * j] = bf4(t); t.x = a.z; t.y = a.w; va[2 * j + 1] = bf4(t);
;             t.x = b.x; t.y = b.y; vb[2 * j] = bf4(t); t.x = b.z; t.y = b.w; vb[2 * j + 1] = bf4(t);
;         }
; #pragma unroll
;         for (int j = 0; j < 4; ++j) { sa += (va[j][0] * va[j][0] + va[j][1] * va[j][1]) + (va[j][2] * va[j][2] + va[j][3] * va[j][3]); sb += (vb[j][0] * vb[j][0] + vb[j][1] * vb[j][1]) + (vb[j][2] * vb[j][2] + vb[j][3] * vb[j][3]); }
; #pragma unroll
;         for (int o = 1; o < 64; o <<= 1) { sa += __shfl_xor(sa, o); sb += __shfl_xor(sb, o); }
;         norm_row16_finish(m, va, sa, gain, mod, shofs, scofs, XN, lane);
;         if (two) norm_row16_finish(m2, vb, sb, gain, mod, shofs, scofs, XN, lane);
.LBB0_671:
	global_load_dwordx4 v[10:13], v[8:9], off offset:1024
	global_load_dwordx4 v[14:17], v[8:9], off
	s_add_i32 s10, s35, s7
	s_cmp_lt_i32 s10, 0x8800
	s_cselect_b32 s12, s10, s7
	s_add_i32 s14, s7, 0xffff8000
	s_ashr_i32 s13, s12, 31
	s_lshr_b32 s14, s14, 6
	s_ashr_i32 s11, s7, 13
	s_lshl_b64 s[12:13], s[12:13], 11
	s_add_i32 s14, s14, 4
	s_cmp_lt_i32 s7, 0x8000
	s_cselect_b32 s11, s11, s14
	s_waitcnt lgkmcnt(0)
	v_lshl_add_u64 v[36:37], v[4:5], 0, s[12:13]
	s_mul_hi_i32 s12, s11, 0x9000
	s_mul_i32 s11, s11, 0x9000
	s_add_u32 s14, s30, s11
	s_addc_u32 s15, s31, s12
	s_lshl_b32 s11, s17, 2
	s_add_u32 s12, s14, s11
	v_lshlrev_b32_e32 v31, 2, v0
	s_addc_u32 s13, s15, 0
	global_load_dwordx4 v[18:21], v[2:3], off offset:16
	global_load_dwordx4 v[22:25], v[2:3], off
	global_load_dwordx4 v[32:35], v[36:37], off
	s_nop 0
	global_load_dwordx4 v[36:39], v[36:37], off offset:1024
	s_nop 0
	global_load_dwordx4 v[40:43], v31, s[12:13] offset:16
	global_load_dwordx4 v[44:47], v31, s[12:13]
	s_lshl_b32 s18, s16, 2
	s_add_u32 s14, s14, s18
	s_addc_u32 s15, s15, 0
	global_load_dwordx4 v[48:51], v31, s[14:15] offset:16
	global_load_dwordx4 v[52:55], v31, s[14:15]
	s_mov_b32 s19, 0xe9c00000
	s_cmp_gt_i32 s10, 0x87ff
	s_waitcnt vmcnt(9)
	v_lshlrev_b32_e32 v64, 16, v12
	v_and_b32_e32 v76, 0xffff0000, v12
	v_lshlrev_b32_e32 v66, 16, v13
	v_and_b32_e32 v67, 0xffff0000, v13
	s_waitcnt vmcnt(8)
	v_lshlrev_b32_e32 v12, 16, v14
	v_and_b32_e32 v13, 0xffff0000, v14
	v_lshlrev_b32_e32 v14, 16, v15
	v_and_b32_e32 v15, 0xffff0000, v15
	v_lshlrev_b32_e32 v57, 16, v17
	v_lshlrev_b32_e32 v56, 16, v16
	v_and_b32_e32 v17, 0xffff0000, v17
	v_and_b32_e32 v16, 0xffff0000, v16
	v_lshlrev_b32_e32 v68, 16, v10
	v_and_b32_e32 v69, 0xffff0000, v10
	v_mul_f32_e32 v10, v12, v12
	v_mul_f32_e32 v58, v14, v14
	v_lshlrev_b32_e32 v70, 16, v11
	v_and_b32_e32 v71, 0xffff0000, v11
	v_pk_mul_f32 v[60:61], v[16:17], v[16:17]
	v_pk_fma_f32 v[10:11], v[12:13], v[12:13], v[10:11] op_sel_hi:[1,1,0]
	v_pk_fma_f32 v[58:59], v[14:15], v[14:15], v[58:59] op_sel_hi:[1,1,0]
	v_mul_f32_e32 v62, v68, v68
	v_mul_f32_e32 v72, v70, v70
	v_mov_b32_e32 v74, v64
	v_pk_fma_f32 v[60:61], v[56:57], v[56:57], v[60:61]
	v_mov_b32_e32 v65, v11
	v_mov_b32_e32 v75, v59
	v_pk_fma_f32 v[62:63], v[68:69], v[68:69], v[62:63] op_sel_hi:[1,1,0]
	v_pk_fma_f32 v[72:73], v[70:71], v[70:71], v[72:73] op_sel_hi:[1,1,0]
	v_pk_add_f32 v[60:61], v[60:61], v[60:61] op_sel_hi:[0,1]
	v_pk_add_f32 v[10:11], v[10:11], v[58:59]
	v_pk_mul_f32 v[58:59], v[64:65], v[74:75]
	v_mul_f32_e32 v62, v66, v66
	v_mul_f32_e32 v72, v67, v67
	v_mul_f32_e32 v60, v76, v76
	v_mov_b32_e32 v59, v11
	v_pk_add_f32 v[62:63], v[62:63], v[72:73]
	v_pk_add_f32 v[10:11], v[58:59], v[60:61]
	s_waitcnt vmcnt(2)
	v_pk_add_f32 v[44:45], v[44:45], 1.0 op_sel_hi:[1,0]
	v_pk_add_f32 v[10:11], v[10:11], v[62:63]
	v_pk_add_f32 v[42:43], v[42:43], 1.0 op_sel_hi:[1,0]
	v_add_f32_e32 v10, v10, v11
	v_pk_add_f32 v[40:41], v[40:41], 1.0 op_sel_hi:[1,0]
	v_add_co_u32_e32 v58, vcc, s19, v8
	v_mov_b32_e32 v65, v76
	s_waitcnt lgkmcnt(0)
	s_nop 1
	v_add_f32_dpp v10, v10, v10 quad_perm:[1,0,3,2] row_mask:0xf bank_mask:0xf
	v_addc_co_u32_e32 v59, vcc, -1, v9, vcc
	s_waitcnt lgkmcnt(0)
	s_nop 1
	v_add_f32_dpp v10, v10, v10 quad_perm:[2,3,0,1] row_mask:0xf bank_mask:0xf
	s_waitcnt lgkmcnt(0)
	s_nop 1
	v_add_f32_dpp v10, v10, v10 row_half_mirror row_mask:0xf bank_mask:0xf
	s_waitcnt lgkmcnt(0)
	s_nop 1
	v_add_f32_dpp v10, v10, v10 row_mirror row_mask:0xf bank_mask:0xf
	v_mov_b32_e32 v11, v10
	s_nop 1
	v_permlane16_swap_b32_e32 v11, v10
	s_nop 1
	s_waitcnt lgkmcnt(0)
	v_add_f32_e32 v60, v10, v11
	v_mov_b32_e32 v61, v60
	s_nop 1
	v_permlane32_swap_b32_e32 v61, v60
	s_nop 1
	v_mov_b32_e32 v10, v57
	v_mov_b32_e32 v11, v17
	v_mov_b32_e32 v57, v16
	v_pk_add_f32 v[16:17], v[46:47], 1.0 op_sel_hi:[1,0]
	s_waitcnt lgkmcnt(0)
	v_add_f32_e32 v46, v60, v61
	v_fmamk_f32 v46, v46, 0x3a800000, v195
	v_rsq_f32_e32 v72, v46
	s_nop 0
	v_pk_mul_f32 v[14:15], v[14:15], v[72:73] op_sel_hi:[1,0]
	v_pk_mul_f32 v[12:13], v[12:13], v[72:73] op_sel_hi:[1,0]
	v_pk_mul_f32 v[10:11], v[10:11], v[72:73] op_sel_hi:[1,0]
	v_pk_mul_f32 v[46:47], v[56:57], v[72:73] op_sel_hi:[1,0]
	v_pk_mul_f32 v[12:13], v[22:23], v[12:13]
	v_pk_mul_f32 v[14:15], v[24:25], v[14:15]
	v_pk_mul_f32 v[18:19], v[18:19], v[46:47]
	v_pk_mul_f32 v[10:11], v[20:21], v[10:11]
	s_waitcnt vmcnt(0)
	v_pk_fma_f32 v[14:15], v[16:17], v[14:15], v[54:55]
	v_pk_fma_f32 v[12:13], v[44:45], v[12:13], v[52:53]
	v_pk_fma_f32 v[16:17], v[42:43], v[10:11], v[50:51]
	v_pk_fma_f32 v[18:19], v[40:41], v[18:19], v[48:49]
	v_cvt_pk_bf16_f32 v10, v12, v13
	v_cvt_pk_bf16_f32 v11, v14, v15
	v_cvt_pk_bf16_f32 v12, v18, v19
	v_cvt_pk_bf16_f32 v13, v16, v17
	global_store_dwordx4 v[58:59], v[10:13], off
	global_load_dwordx4 v[40:43], v31, s[12:13] offset:2048
	global_load_dwordx4 v[48:51], v31, s[12:13] offset:2064
	global_load_dwordx4 v[44:47], v[2:3], off offset:2048
	global_load_dwordx4 v[52:55], v[2:3], off offset:2064
	s_nop 0
	global_load_dwordx4 v[56:59], v31, s[14:15] offset:2064
	global_load_dwordx4 v[60:63], v31, s[14:15] offset:2048
	v_and_b32_e32 v21, 0xffff0000, v32
	v_and_b32_e32 v25, 0xffff0000, v33
	v_and_b32_e32 v19, 0xffff0000, v34
	v_and_b32_e32 v23, 0xffff0000, v35
	v_lshlrev_b32_e32 v20, 16, v32
	v_lshlrev_b32_e32 v24, 16, v33
	v_lshlrev_b32_e32 v18, 16, v34
	v_lshlrev_b32_e32 v22, 16, v35
	v_and_b32_e32 v15, 0xffff0000, v36
	v_and_b32_e32 v17, 0xffff0000, v37
	v_mul_f32_e32 v32, v21, v21
	v_mul_f32_e32 v33, v25, v25
	v_mul_f32_e32 v34, v19, v19
	v_mul_f32_e32 v35, v23, v23
	v_lshlrev_b32_e32 v14, 16, v36
	v_lshlrev_b32_e32 v16, 16, v37
	v_and_b32_e32 v11, 0xffff0000, v38
	v_and_b32_e32 v13, 0xffff0000, v39
	v_mul_f32_e32 v36, v15, v15
	v_mul_f32_e32 v37, v17, v17
	v_fmac_f32_e32 v32, v20, v20
	v_fmac_f32_e32 v33, v24, v24
	v_fmac_f32_e32 v34, v18, v18
	v_fmac_f32_e32 v35, v22, v22
	v_lshlrev_b32_e32 v10, 16, v38
	v_lshlrev_b32_e32 v12, 16, v39
	v_mul_f32_e32 v38, v11, v11
	v_mul_f32_e32 v39, v13, v13
	v_fmac_f32_e32 v36, v14, v14
	v_fmac_f32_e32 v37, v16, v16
	v_add_f32_e32 v32, v32, v33
	v_add_f32_e32 v33, v34, v35
	v_fmac_f32_e32 v38, v10, v10
	v_fmac_f32_e32 v39, v12, v12
	v_add_f32_e32 v34, v36, v37
	v_add_f32_e32 v32, v32, v33
	v_add_f32_e32 v35, v38, v39
	v_add_f32_e32 v32, v32, v34
	v_add_f32_e32 v32, v35, v32
	v_pk_mul_f32 v[34:35], v[70:71], v[72:73] op_sel_hi:[1,0]
	v_pk_mul_f32 v[36:37], v[68:69], v[72:73] op_sel_hi:[1,0]
	v_pk_mul_f32 v[66:67], v[66:67], v[72:73] op_sel_hi:[1,0]
	v_pk_mul_f32 v[64:65], v[64:65], v[72:73] op_sel_hi:[1,0]
	s_waitcnt lgkmcnt(0)
; DI unsigned pk2(float lo, float hi) { f32x2 v = {lo, hi}; bf16x2_t b = __builtin_convertvector(v, bf16x2_t); return __builtin_bit_cast(unsigned, b); }
; DI void norm_row16_finish(int m, const f32x4 (&v)[4], float s, const float* gain, const float* mod, int shofs, int scofs, bf16_t* XN, int lane) {
;     const float* mb = mod + (size_t)row_batch(m) * NMOD;
;     const float inv = __builtin_amdgcn_rsqf(s * (1.f / D) + EPS);
; #pragma unroll
;     for (int j = 0; j < 2; ++j) {
;         const int c = 8 * (64 * j + lane);
;         u32x4 w;
; #pragma unroll
;         for (int q = 0; q < 2; ++q) {
;             const f32x4 g4 = *(const f32x4*)(gain + c + 4 * q), sc4 = *(const f32x4*)(mb + scofs + c + 4 * q), sh4 = *(const f32x4*)(mb + shofs + c + 4 * q);
;             const f32x4 o = v[2 * j + q] * inv * g4 * (sc4 + 1.f) + sh4;
;             if (q == 0) { w.x = pk2(o[0], o[1]); w.y = pk2(o[2], o[3]); } else { w.z = pk2(o[0], o[1]); w.w = pk2(o[2], o[3]); }
;         }
;         *(u32x4*)(XN + (size_t)m * D + c) = w;
;     }
; DI void norm_phase_b16(const bf16_t* src, const float* gain, const float* mod, int shofs, int scofs, bf16_t* XN, int wave, int lane) {
;     ...
;     for (int m = gw; m < M; m += 2 * NGW) {
;         const int m2 = m + NGW; const bool two = m2 < M; const int mb2 = two ? m2 : m;
;         f32x4 va[4], vb[4]; float sa = 0.f, sb = 0.f;
; #pragma unroll
;         for (int j = 0; j < 2; ++j) {
;             const u32x4 a = *(const u32x4*)(src + (size_t)m * D + 8 * (64 * j + lane)), b = *(const u32x4*)(src + (size_t)mb2 * D + 8 * (64 * j + lane));
;             u32x2 t; t.x = a.x; t.y = a.y; va[2 * j] = bf4(t); t.x = a.z; t.y = a.w; va[2 * j + 1] = bf4(t);
;             t.x = b.x; t.y = b.y; vb[2 * j] = bf4(t); t.x = b.z; t.y = b.w; vb[2 * j + 1] = bf4(t);
;         }
; #pragma unroll
;         for (int j = 0; j < 4; ++j) { sa += (va[j][0] * va[j][0] + va[j][1] * va[j][1]) + (va[j][2] * va[j][2] + va[j][3] * va[j][3]); sb += (vb[j][0] * vb[j][0] + vb[j][1] * vb[j][1]) + (vb[j][2] * vb[j][2] + vb[j][3] * vb[j][3]); }
; #pragma unroll
;         for (int o = 1; o < 64; o <<= 1) { sa += __shfl_xor(sa, o); sb += __shfl_xor(sb, o); }
;         norm_row16_finish(m, va, sa, gain, mod, shofs, scofs, XN, lane);
;         if (two) norm_row16_finish(m2, vb, sb, gain, mod, shofs, scofs, XN, lane);
	s_nop 1
	v_add_f32_dpp v32, v32, v32 quad_perm:[1,0,3,2] row_mask:0xf bank_mask:0xf
	v_add_co_u32_e32 v38, vcc, 0xe9c01000, v8
	s_waitcnt lgkmcnt(0)
	s_nop 1
	v_add_f32_dpp v32, v32, v32 quad_perm:[2,3,0,1] row_mask:0xf bank_mask:0xf
	v_addc_co_u32_e32 v39, vcc, -1, v9, vcc
	s_waitcnt lgkmcnt(0)
	s_nop 1
	v_add_f32_dpp v32, v32, v32 row_half_mirror row_mask:0xf bank_mask:0xf
	s_waitcnt lgkmcnt(0)
	s_nop 1
	v_add_f32_dpp v32, v32, v32 row_mirror row_mask:0xf bank_mask:0xf
	v_mov_b32_e32 v33, v32
	s_nop 1
	v_permlane16_swap_b32_e32 v33, v32
	s_nop 1
	s_waitcnt lgkmcnt(0)
	v_add_f32_e32 v32, v32, v33
	ds_bpermute_b32 v33, v30, v32
	s_waitcnt vmcnt(5)
	v_pk_add_f32 v[42:43], v[42:43], 1.0 op_sel_hi:[1,0]
	v_pk_add_f32 v[40:41], v[40:41], 1.0 op_sel_hi:[1,0]
	s_waitcnt vmcnt(3)
	v_pk_mul_f32 v[36:37], v[36:37], v[44:45]
	v_pk_mul_f32 v[34:35], v[34:35], v[46:47]
	v_pk_add_f32 v[44:45], v[50:51], 1.0 op_sel_hi:[1,0]
	v_pk_add_f32 v[46:47], v[48:49], 1.0 op_sel_hi:[1,0]
	s_waitcnt vmcnt(2)
	v_pk_mul_f32 v[48:49], v[64:65], v[52:53]
	v_pk_mul_f32 v[50:51], v[66:67], v[54:55]
	s_waitcnt vmcnt(0)
	v_pk_fma_f32 v[42:43], v[42:43], v[34:35], v[62:63]
	v_pk_fma_f32 v[34:35], v[40:41], v[36:37], v[60:61]
	v_pk_fma_f32 v[40:41], v[44:45], v[50:51], v[58:59]
	v_pk_fma_f32 v[36:37], v[46:47], v[48:49], v[56:57]
	v_cvt_pk_bf16_f32 v34, v34, v35
	v_cvt_pk_bf16_f32 v35, v42, v43
	v_cvt_pk_bf16_f32 v36, v36, v37
	v_cvt_pk_bf16_f32 v37, v40, v41
	global_store_dwordx4 v[38:39], v[34:37], off offset:-3072
	s_cbranch_scc1 .LBB0_670
	s_add_i32 s13, s10, 0xffff8000
	s_lshr_b32 s13, s13, 6
	s_ashr_i32 s12, s10, 13
	s_add_i32 s13, s13, 4
	s_cmp_lt_i32 s10, 0x8000
	s_cselect_b32 s12, s12, s13
	s_mul_hi_i32 s13, s12, 0x9000
	s_mul_i32 s12, s12, 0x9000
	s_add_u32 s14, s30, s12
	s_addc_u32 s15, s31, s13
	s_add_u32 s12, s14, s11
	s_addc_u32 s13, s15, 0
	s_add_u32 s14, s14, s18
	global_load_dwordx4 v[34:37], v[2:3], off offset:16
	global_load_dwordx4 v[38:41], v[2:3], off
	global_load_dwordx4 v[42:45], v31, s[12:13]
	global_load_dwordx4 v[46:49], v31, s[12:13] offset:16
	s_addc_u32 s15, s15, 0
	global_load_dwordx4 v[50:53], v31, s[14:15]
	global_load_dwordx4 v[54:57], v31, s[14:15] offset:16
	s_waitcnt lgkmcnt(0)
	v_add_f32_e32 v32, v32, v33
	v_fmamk_f32 v32, v32, 0x3a800000, v195
	v_rsq_f32_e32 v58, v32
	s_ashr_i32 s11, s10, 31
	s_lshl_b64 s[10:11], s[10:11], 11
	v_lshl_add_u64 v[60:61], v[6:7], 0, s[10:11]
	v_pk_mul_f32 v[24:25], v[24:25], v[58:59] op_sel_hi:[1,0]
	v_pk_mul_f32 v[20:21], v[20:21], v[58:59] op_sel_hi:[1,0]
	v_pk_mul_f32 v[22:23], v[22:23], v[58:59] op_sel_hi:[1,0]
	v_pk_mul_f32 v[18:19], v[18:19], v[58:59] op_sel_hi:[1,0]
	v_pk_mul_f32 v[16:17], v[16:17], v[58:59] op_sel_hi:[1,0]
	v_pk_mul_f32 v[14:15], v[14:15], v[58:59] op_sel_hi:[1,0]
	v_pk_mul_f32 v[12:13], v[12:13], v[58:59] op_sel_hi:[1,0]
	v_pk_mul_f32 v[10:11], v[10:11], v[58:59] op_sel_hi:[1,0]
	s_waitcnt vmcnt(5)
	v_pk_mul_f32 v[18:19], v[18:19], v[34:35]
	s_waitcnt vmcnt(4)
	v_pk_mul_f32 v[20:21], v[20:21], v[38:39]
	v_pk_mul_f32 v[24:25], v[24:25], v[40:41]
	v_pk_mul_f32 v[22:23], v[22:23], v[36:37]
	s_waitcnt vmcnt(3)
	v_pk_add_f32 v[32:33], v[44:45], 1.0 op_sel_hi:[1,0]
	v_pk_add_f32 v[34:35], v[42:43], 1.0 op_sel_hi:[1,0]
	s_waitcnt vmcnt(2)
	v_pk_add_f32 v[36:37], v[48:49], 1.0 op_sel_hi:[1,0]
	v_pk_add_f32 v[38:39], v[46:47], 1.0 op_sel_hi:[1,0]
	s_waitcnt vmcnt(1)
	v_pk_fma_f32 v[24:25], v[32:33], v[24:25], v[52:53]
	v_pk_fma_f32 v[20:21], v[34:35], v[20:21], v[50:51]
	s_waitcnt vmcnt(0)
	v_pk_fma_f32 v[22:23], v[36:37], v[22:23], v[56:57]
	v_pk_fma_f32 v[32:33], v[38:39], v[18:19], v[54:55]
	v_cvt_pk_bf16_f32 v18, v20, v21
	v_cvt_pk_bf16_f32 v19, v24, v25
	v_cvt_pk_bf16_f32 v20, v32, v33
	v_cvt_pk_bf16_f32 v21, v22, v23
	global_store_dwordx4 v[60:61], v[18:21], off
	global_load_dwordx4 v[18:21], v31, s[12:13] offset:2048
	s_nop 0
	global_load_dwordx4 v[22:25], v[2:3], off offset:2048
	global_load_dwordx4 v[32:35], v31, s[12:13] offset:2064
	global_load_dwordx4 v[36:39], v[2:3], off offset:2064
	global_load_dwordx4 v[40:43], v31, s[14:15] offset:2048
	global_load_dwordx4 v[44:47], v31, s[14:15] offset:2064
	s_waitcnt vmcnt(5)
	v_pk_add_f32 v[20:21], v[20:21], 1.0 op_sel_hi:[1,0]
	v_pk_add_f32 v[18:19], v[18:19], 1.0 op_sel_hi:[1,0]
	s_waitcnt vmcnt(4)
	v_pk_mul_f32 v[14:15], v[14:15], v[22:23]
	v_pk_mul_f32 v[16:17], v[16:17], v[24:25]
	s_waitcnt vmcnt(3)
	v_pk_add_f32 v[22:23], v[34:35], 1.0 op_sel_hi:[1,0]
	v_pk_add_f32 v[24:25], v[32:33], 1.0 op_sel_hi:[1,0]
	s_waitcnt vmcnt(2)
	v_pk_mul_f32 v[10:11], v[10:11], v[36:37]
	v_pk_mul_f32 v[12:13], v[12:13], v[38:39]
	s_waitcnt vmcnt(1)
	v_pk_fma_f32 v[16:17], v[20:21], v[16:17], v[42:43]
	v_pk_fma_f32 v[14:15], v[18:19], v[14:15], v[40:41]
	s_waitcnt vmcnt(0)
	v_pk_fma_f32 v[18:19], v[22:23], v[12:13], v[46:47]
	v_pk_fma_f32 v[12:13], v[24:25], v[10:11], v[44:45]
	v_cvt_pk_bf16_f32 v10, v14, v15
	v_cvt_pk_bf16_f32 v11, v16, v17
	v_cvt_pk_bf16_f32 v12, v12, v13
	v_cvt_pk_bf16_f32 v13, v18, v19
	global_store_dwordx4 v[60:61], v[10:13], off offset:1024
	s_branch .LBB0_670

; DI void norm_row16_finish(int m, const f32x4 (&v)[4], float s, const float* gain, const float* mod, int shofs, int scofs, bf16_t* XN, int lane) {
;     const float* mb = mod + (size_t)row_batch(m) * NMOD;
;     const float inv = __builtin_amdgcn_rsqf(s * (1.f / D) + EPS);
; #pragma unroll
;     for (int j = 0; j < 2; ++j) {
;         const int c = 8 * (64 * j + lane);
;         u32x4 w;
; #pragma unroll
;         for (int q = 0; q < 2; ++q) {
;             const f32x4 g4 = *(const f32x4*)(gain + c + 4 * q), sc4 = *(const f32x4*)(mb + scofs + c + 4 * q), sh4 = *(const f32x4*)(mb + shofs + c + 4 * q);
;             const f32x4 o = v[2 * j + q] * inv * g4 * (sc4 + 1.f) + sh4;
;             if (q == 0) { w.x = pk2(o[0], o[1]); w.y = pk2(o[2], o[3]); } else { w.z = pk2(o[0], o[1]); w.w = pk2(o[2], o[3]); }
;         }
;         *(u32x4*)(XN + (size_t)m * D + c) = w;
;     }
; DI void norm_phase_f32w(const float* srcP, const float* srcS, const float* gain, const float* mod, int shofs, int scofs, bf16_t* XN, int wave, int lane) {
;     const int gw = blockIdx.x * 8 + wave, NGW = gridDim.x * 8;
;     for (int m = gw; m < M; m += 2 * NGW) {
;         const int m2 = m + NGW; const bool two = m2 < M; const int mb2 = two ? m2 : m;
;         const float* xa = m < MP ? srcP + (size_t)m * D : srcS + (size_t)(m - MP) * D;
;         const float* xb = mb2 < MP ? srcP + (size_t)mb2 * D : srcS + (size_t)(mb2 - MP) * D;
;         f32x4 va[4], vb[4]; float sa = 0.f, sb = 0.f;
; #pragma unroll
;         for (int j = 0; j < 2; ++j) { const int c = 8 * (64 * j + lane);
;             va[2 * j] = *(const f32x4*)(xa + c); va[2 * j + 1] = *(const f32x4*)(xa + c + 4); vb[2 * j] = *(const f32x4*)(xb + c); vb[2 * j + 1] = *(const f32x4*)(xb + c + 4); }
; #pragma unroll
;         for (int j = 0; j < 4; ++j) { sa += (va[j][0] * va[j][0] + va[j][1] * va[j][1]) + (va[j][2] * va[j][2] + va[j][3] * va[j][3]); sb += (vb[j][0] * vb[j][0] + vb[j][1] * vb[j][1]) + (vb[j][2] * vb[j][2] + vb[j][3] * vb[j][3]); }
; #pragma unroll
;         for (int o = 1; o < 64; o <<= 1) { sa += __shfl_xor(sa, o); sb += __shfl_xor(sb, o); }
;         norm_row16_finish(m, va, sa, gain, mod, shofs, scofs, XN, lane);
;         if (two) norm_row16_finish(m2, vb, sb, gain, mod, shofs, scofs, XN, lane);
.LBB0_678:
	s_add_i32 s20, s35, s6
	s_cmp_lt_i32 s20, 0x8800
	s_cselect_b32 s12, s20, s6
	s_add_i32 s10, s6, 0xffff8000
	s_lshr_b32 s11, s10, 6
	s_ashr_i32 s13, s6, 13
	s_add_i32 s14, s11, 4
	s_cmp_lt_i32 s6, 0x8000
	s_cselect_b32 s11, s7, 0
	s_cselect_b32 s10, s6, s10
	s_cselect_b32 s15, s16, s18
	s_cselect_b32 s21, s17, s19
	s_cselect_b32 s13, s13, s14
	s_lshl_b64 s[10:11], s[10:11], 12
	s_add_u32 s10, s21, s10
	s_addc_u32 s11, s15, s11
	v_lshlrev_b32_e32 v34, 2, v24
	s_waitcnt lgkmcnt(0)
	global_load_dwordx4 v[36:39], v34, s[10:11]
	global_load_dwordx4 v[40:43], v34, s[10:11] offset:16
	global_load_dwordx4 v[4:7], v34, s[10:11] offset:2064
	global_load_dwordx4 v[12:15], v34, s[10:11] offset:2048
	s_add_i32 s10, s12, 0xffff8000
	s_ashr_i32 s11, s12, 31
	s_cmp_lt_i32 s12, 0x8000
	s_cselect_b32 s11, s11, 0
	s_cselect_b32 s10, s12, s10
	s_cselect_b32 s12, s16, s18
	s_cselect_b32 s14, s17, s19
	s_lshl_b64 s[10:11], s[10:11], 12
	s_add_u32 s14, s14, s10
	s_mul_hi_i32 s21, s13, 0x9000
	s_mul_i32 s13, s13, 0x9000
	s_addc_u32 s15, s12, s11
	s_add_u32 s10, s30, s13
	s_addc_u32 s11, s31, s21
	s_add_u32 s12, s10, 0x1000
	s_addc_u32 s13, s11, 0
	global_load_dwordx4 v[44:47], v34, s[12:13]
	global_load_dwordx4 v[48:51], v34, s[12:13] offset:16
	global_load_dwordx4 v[52:55], v[26:27], off
	global_load_dwordx4 v[56:59], v[26:27], off offset:16
	global_load_dwordx4 v[60:63], v34, s[10:11]
	global_load_dwordx4 v[64:67], v34, s[10:11] offset:16
	s_cmp_gt_i32 s20, 0x87ff
	s_waitcnt vmcnt(9)
	v_pk_mul_f32 v[0:1], v[38:39], v[38:39]
	v_pk_mul_f32 v[2:3], v[36:37], v[36:37]
	s_waitcnt vmcnt(8)
	v_pk_mul_f32 v[8:9], v[42:43], v[42:43]
	v_pk_mul_f32 v[10:11], v[40:41], v[40:41]
	v_pk_mov_b32 v[20:21], v[2:3], v[0:1] op_sel:[1,0]
	v_mov_b32_e32 v3, v1
	v_pk_mov_b32 v[0:1], v[10:11], v[8:9] op_sel:[1,0]
	v_mov_b32_e32 v11, v9
	s_waitcnt vmcnt(7)
	v_mul_f32_e32 v19, v4, v4
	s_waitcnt vmcnt(6)
	v_mul_f32_e32 v16, v13, v13
	v_mul_f32_e32 v18, v15, v15
	v_pk_add_f32 v[2:3], v[20:21], v[2:3]
	v_pk_add_f32 v[0:1], v[0:1], v[10:11]
	v_mul_f32_e32 v22, v5, v5
	v_mul_f32_e32 v23, v6, v6
	v_mul_f32_e32 v35, v7, v7
	v_pk_fma_f32 v[8:9], v[12:13], v[12:13], v[16:17] op_sel_hi:[1,1,0]
	v_pk_fma_f32 v[16:17], v[14:15], v[14:15], v[18:19] op_sel_hi:[1,1,0]
	v_pk_add_f32 v[2:3], v[2:3], v[2:3] op_sel:[0,1] op_sel_hi:[1,0]
	v_pk_add_f32 v[0:1], v[0:1], v[0:1] op_sel:[0,1] op_sel_hi:[1,0]
	v_mov_b32_e32 v9, v23
	v_mov_b32_e32 v17, v35
	v_mov_b32_e32 v3, v19
	v_mov_b32_e32 v1, v22
	v_pk_add_f32 v[8:9], v[8:9], v[16:17]
	v_pk_add_f32 v[0:1], v[2:3], v[0:1]
	s_waitcnt vmcnt(5)
	v_pk_add_f32 v[46:47], v[46:47], 1.0 op_sel_hi:[1,0]
	v_pk_add_f32 v[0:1], v[0:1], v[8:9]
	global_load_dwordx4 v[20:23], v34, s[14:15]
	global_load_dwordx4 v[16:19], v34, s[14:15] offset:16
	global_load_dwordx4 v[8:11], v34, s[14:15] offset:2048
	v_add_f32_e32 v0, v0, v1
	v_pk_add_f32 v[44:45], v[44:45], 1.0 op_sel_hi:[1,0]
	s_waitcnt vmcnt(7)
	v_pk_add_f32 v[50:51], v[50:51], 1.0 op_sel_hi:[1,0]
	v_pk_add_f32 v[48:49], v[48:49], 1.0 op_sel_hi:[1,0]
	s_waitcnt lgkmcnt(0)
	s_nop 1
	v_add_f32_dpp v35, v0, v0 quad_perm:[1,0,3,2] row_mask:0xf bank_mask:0xf
	global_load_dwordx4 v[0:3], v34, s[14:15] offset:2064
	s_waitcnt lgkmcnt(0)
	s_nop 1
	v_add_f32_dpp v35, v35, v35 quad_perm:[2,3,0,1] row_mask:0xf bank_mask:0xf
	s_waitcnt lgkmcnt(0)
	s_nop 1
	v_add_f32_dpp v35, v35, v35 row_half_mirror row_mask:0xf bank_mask:0xf
	s_waitcnt lgkmcnt(0)
	s_nop 1
	v_add_f32_dpp v35, v35, v35 row_mirror row_mask:0xf bank_mask:0xf
	v_mov_b32_e32 v70, v35
	s_nop 1
	v_permlane16_swap_b32_e32 v70, v35
	s_nop 1
	v_lshl_add_u64 v[68:69], s[4:5], 0, v[160:161]
	v_add_co_u32_e32 v68, vcc, s71, v68
	s_waitcnt lgkmcnt(0)
	v_add_f32_e32 v35, v35, v70
	v_mov_b32_e32 v70, v35
	s_nop 1
	v_permlane32_swap_b32_e32 v70, v35
	s_nop 1
	v_addc_co_u32_e32 v69, vcc, 0, v69, vcc
	s_waitcnt lgkmcnt(0)
	v_add_f32_e32 v35, v35, v70
	v_fmamk_f32 v35, v35, 0x3a800000, v195
	v_rsq_f32_e32 v70, v35
	s_waitcnt vmcnt(3)
	v_mul_f32_e32 v35, v21, v21
	v_pk_mul_f32 v[38:39], v[38:39], v[70:71] op_sel_hi:[1,0]
	v_pk_mul_f32 v[36:37], v[36:37], v[70:71] op_sel_hi:[1,0]
	v_pk_mul_f32 v[42:43], v[42:43], v[70:71] op_sel_hi:[1,0]
	v_pk_mul_f32 v[40:41], v[40:41], v[70:71] op_sel_hi:[1,0]
	v_pk_mul_f32 v[36:37], v[52:53], v[36:37]
	v_pk_mul_f32 v[38:39], v[54:55], v[38:39]
	v_pk_mul_f32 v[40:41], v[56:57], v[40:41]
	v_pk_mul_f32 v[42:43], v[58:59], v[42:43]
	v_pk_fma_f32 v[38:39], v[46:47], v[38:39], v[62:63]
	v_pk_fma_f32 v[36:37], v[44:45], v[36:37], v[60:61]
	v_pk_fma_f32 v[42:43], v[50:51], v[42:43], v[66:67]
	v_pk_fma_f32 v[40:41], v[48:49], v[40:41], v[64:65]
	v_cvt_pk_bf16_f32 v36, v36, v37
	v_cvt_pk_bf16_f32 v37, v38, v39
	v_cvt_pk_bf16_f32 v38, v40, v41
	v_cvt_pk_bf16_f32 v39, v42, v43
	global_store_dwordx4 v[68:69], v[36:39], off
	global_load_dwordx4 v[38:41], v33, s[12:13]
	s_nop 0
	global_load_dwordx4 v[42:45], v[26:27], off offset:2048
	global_load_dwordx4 v[46:49], v33, s[12:13] offset:16
	global_load_dwordx4 v[50:53], v[26:27], off offset:2064
	global_load_dwordx4 v[54:57], v34, s[10:11] offset:2048
	global_load_dwordx4 v[58:61], v34, s[10:11] offset:2064
	v_mul_f32_e32 v36, v23, v23
	s_waitcnt vmcnt(9)
	v_mul_f32_e32 v37, v17, v17
	v_mul_f32_e32 v62, v19, v19
	s_waitcnt vmcnt(8)
	v_mul_f32_e32 v63, v9, v9
	v_mul_f32_e32 v64, v11, v11
	v_fmac_f32_e32 v35, v20, v20
	v_fmac_f32_e32 v36, v22, v22
	v_fmac_f32_e32 v37, v16, v16
	v_fmac_f32_e32 v62, v18, v18
	s_waitcnt vmcnt(7)
; DI unsigned pk2(float lo, float hi) { f32x2 v = {lo, hi}; bf16x2_t b = __builtin_convertvector(v, bf16x2_t); return __builtin_bit_cast(unsigned, b); }
; DI void norm_row16_finish(int m, const f32x4 (&v)[4], float s, const float* gain, const float* mod, int shofs, int scofs, bf16_t* XN, int lane) {
;     const float* mb = mod + (size_t)row_batch(m) * NMOD;
;     const float inv = __builtin_amdgcn_rsqf(s * (1.f / D) + EPS);
; #pragma unroll
;     for (int j = 0; j < 2; ++j) {
;         const int c = 8 * (64 * j + lane);
;         u32x4 w;
; #pragma unroll
;         for (int q = 0; q < 2; ++q) {
;             const f32x4 g4 = *(const f32x4*)(gain + c + 4 * q), sc4 = *(const f32x4*)(mb + scofs + c + 4 * q), sh4 = *(const f32x4*)(mb + shofs + c + 4 * q);
;             const f32x4 o = v[2 * j + q] * inv * g4 * (sc4 + 1.f) + sh4;
;             if (q == 0) { w.x = pk2(o[0], o[1]); w.y = pk2(o[2], o[3]); } else { w.z = pk2(o[0], o[1]); w.w = pk2(o[2], o[3]); }
;         }
;         *(u32x4*)(XN + (size_t)m * D + c) = w;
;     }
; DI void norm_phase_f32w(const float* srcP, const float* srcS, const float* gain, const float* mod, int shofs, int scofs, bf16_t* XN, int wave, int lane) {
;     ...
;         for (int j = 0; j < 4; ++j) { sa += (va[j][0] * va[j][0] + va[j][1] * va[j][1]) + (va[j][2] * va[j][2] + va[j][3] * va[j][3]); sb += (vb[j][0] * vb[j][0] + vb[j][1] * vb[j][1]) + (vb[j][2] * vb[j][2] + vb[j][3] * vb[j][3]); }
; #pragma unroll
;         for (int o = 1; o < 64; o <<= 1) { sa += __shfl_xor(sa, o); sb += __shfl_xor(sb, o); }
;         norm_row16_finish(m, va, sa, gain, mod, shofs, scofs, XN, lane);
;         if (two) norm_row16_finish(m2, vb, sb, gain, mod, shofs, scofs, XN, lane);
;     }
	v_mul_f32_e32 v65, v1, v1
	v_mul_f32_e32 v66, v3, v3
	v_fmac_f32_e32 v63, v8, v8
	v_fmac_f32_e32 v64, v10, v10
	v_add_f32_e32 v35, v35, v36
	v_add_f32_e32 v36, v37, v62
	v_fmac_f32_e32 v65, v0, v0
	v_fmac_f32_e32 v66, v2, v2
	v_add_f32_e32 v37, v63, v64
	v_add_f32_e32 v35, v35, v36
	v_add_f32_e32 v62, v65, v66
	v_add_f32_e32 v35, v35, v37
	v_add_f32_e32 v35, v35, v62
	v_pk_mul_f32 v[14:15], v[14:15], v[70:71] op_sel_hi:[1,0]
	v_pk_mul_f32 v[12:13], v[12:13], v[70:71] op_sel_hi:[1,0]
	v_pk_mul_f32 v[6:7], v[6:7], v[70:71] op_sel_hi:[1,0]
	v_pk_mul_f32 v[4:5], v[4:5], v[70:71] op_sel_hi:[1,0]
	s_waitcnt lgkmcnt(0)
	s_nop 1
	v_add_f32_dpp v35, v35, v35 quad_perm:[1,0,3,2] row_mask:0xf bank_mask:0xf
	s_waitcnt lgkmcnt(0)
	s_nop 1
	v_add_f32_dpp v35, v35, v35 quad_perm:[2,3,0,1] row_mask:0xf bank_mask:0xf
	s_waitcnt lgkmcnt(0)
	s_nop 1
	v_add_f32_dpp v35, v35, v35 row_half_mirror row_mask:0xf bank_mask:0xf
	s_waitcnt lgkmcnt(0)
	s_nop 1
	v_add_f32_dpp v35, v35, v35 row_mirror row_mask:0xf bank_mask:0xf
	v_mov_b32_e32 v36, v35
	s_nop 1
	v_permlane16_swap_b32_e32 v36, v35
	s_nop 1
	s_waitcnt lgkmcnt(0)
	v_add_f32_e32 v35, v35, v36
	ds_bpermute_b32 v36, v32, v35
	s_waitcnt vmcnt(5)
	v_pk_add_f32 v[40:41], v[40:41], 1.0 op_sel_hi:[1,0]
	v_pk_add_f32 v[38:39], v[38:39], 1.0 op_sel_hi:[1,0]
	s_waitcnt vmcnt(4)
	v_pk_mul_f32 v[12:13], v[12:13], v[42:43]
	v_pk_mul_f32 v[14:15], v[14:15], v[44:45]
	s_waitcnt vmcnt(3)
	v_pk_add_f32 v[42:43], v[48:49], 1.0 op_sel_hi:[1,0]
	v_pk_add_f32 v[44:45], v[46:47], 1.0 op_sel_hi:[1,0]
	s_waitcnt vmcnt(2)
	v_pk_mul_f32 v[4:5], v[4:5], v[50:51]
	v_pk_mul_f32 v[6:7], v[6:7], v[52:53]
	s_waitcnt vmcnt(1)
	v_pk_fma_f32 v[14:15], v[40:41], v[14:15], v[56:57]
	v_pk_fma_f32 v[12:13], v[38:39], v[12:13], v[54:55]
	s_waitcnt vmcnt(0)
	v_pk_fma_f32 v[38:39], v[42:43], v[6:7], v[60:61]
	v_pk_fma_f32 v[6:7], v[44:45], v[4:5], v[58:59]
	v_cvt_pk_bf16_f32 v4, v12, v13
	v_cvt_pk_bf16_f32 v5, v14, v15
	v_cvt_pk_bf16_f32 v6, v6, v7
	v_cvt_pk_bf16_f32 v7, v38, v39
	global_store_dwordx4 v[68:69], v[4:7], off offset:1024
	s_cbranch_scc1 .LBB0_677
	s_add_i32 s11, s20, 0xffff8000
	s_lshr_b32 s11, s11, 6
	s_ashr_i32 s10, s20, 13
	s_add_i32 s11, s11, 4
	s_cmp_lt_i32 s20, 0x8000
	s_cselect_b32 s10, s10, s11
	s_mul_hi_i32 s11, s10, 0x9000
	s_mul_i32 s10, s10, 0x9000
	s_add_u32 s10, s30, s10
	s_addc_u32 s11, s31, s11
	s_add_u32 s12, s10, 0x1000
	global_load_dwordx4 v[4:7], v[26:27], off offset:16
	global_load_dwordx4 v[12:15], v[26:27], off
	s_addc_u32 s13, s11, 0
	global_load_dwordx4 v[38:41], v34, s[12:13]
	global_load_dwordx4 v[42:45], v34, s[12:13] offset:16
	global_load_dwordx4 v[46:49], v34, s[10:11]
	global_load_dwordx4 v[50:53], v34, s[10:11] offset:16
	s_waitcnt lgkmcnt(0)
	v_add_f32_e32 v35, v35, v36
	v_fmamk_f32 v35, v35, 0x3a800000, v195
	v_rsq_f32_e32 v54, v35
	v_lshl_add_u64 v[36:37], s[8:9], 0, v[160:161]
	v_add_co_u32_e32 v56, vcc, s71, v36
	v_pk_mul_f32 v[22:23], v[22:23], v[54:55] op_sel_hi:[1,0]
	v_pk_mul_f32 v[20:21], v[20:21], v[54:55] op_sel_hi:[1,0]
	v_pk_mul_f32 v[18:19], v[18:19], v[54:55] op_sel_hi:[1,0]
	v_pk_mul_f32 v[16:17], v[16:17], v[54:55] op_sel_hi:[1,0]
	v_addc_co_u32_e32 v57, vcc, 0, v37, vcc
	v_pk_mul_f32 v[10:11], v[10:11], v[54:55] op_sel_hi:[1,0]
	v_pk_mul_f32 v[8:9], v[8:9], v[54:55] op_sel_hi:[1,0]
	v_pk_mul_f32 v[2:3], v[2:3], v[54:55] op_sel_hi:[1,0]
	v_pk_mul_f32 v[0:1], v[0:1], v[54:55] op_sel_hi:[1,0]
	s_waitcnt vmcnt(5)
	v_pk_mul_f32 v[6:7], v[18:19], v[6:7]
	s_waitcnt vmcnt(4)
	v_pk_mul_f32 v[14:15], v[22:23], v[14:15]
	v_pk_mul_f32 v[12:13], v[20:21], v[12:13]
	v_pk_mul_f32 v[4:5], v[16:17], v[4:5]
	s_waitcnt vmcnt(3)
	v_pk_add_f32 v[16:17], v[40:41], 1.0 op_sel_hi:[1,0]
	v_pk_add_f32 v[18:19], v[38:39], 1.0 op_sel_hi:[1,0]
	s_waitcnt vmcnt(2)
	v_pk_add_f32 v[20:21], v[44:45], 1.0 op_sel_hi:[1,0]
	v_pk_add_f32 v[22:23], v[42:43], 1.0 op_sel_hi:[1,0]
	s_waitcnt vmcnt(1)
	v_pk_fma_f32 v[14:15], v[16:17], v[14:15], v[48:49]
	v_pk_fma_f32 v[12:13], v[18:19], v[12:13], v[46:47]
	s_waitcnt vmcnt(0)
	v_pk_fma_f32 v[16:17], v[20:21], v[6:7], v[52:53]
	v_pk_fma_f32 v[6:7], v[22:23], v[4:5], v[50:51]
	v_cvt_pk_bf16_f32 v4, v12, v13
	v_cvt_pk_bf16_f32 v5, v14, v15
	v_cvt_pk_bf16_f32 v6, v6, v7
	v_cvt_pk_bf16_f32 v7, v16, v17
	global_store_dwordx4 v[56:57], v[4:7], off
	global_load_dwordx4 v[4:7], v33, s[12:13]
	s_nop 0
	global_load_dwordx4 v[12:15], v[26:27], off offset:2048
	global_load_dwordx4 v[16:19], v33, s[12:13] offset:16
	global_load_dwordx4 v[20:23], v[26:27], off offset:2064
	global_load_dwordx4 v[36:39], v34, s[10:11] offset:2048
	global_load_dwordx4 v[40:43], v34, s[10:11] offset:2064
	s_waitcnt vmcnt(5)
	v_pk_add_f32 v[6:7], v[6:7], 1.0 op_sel_hi:[1,0]
	v_pk_add_f32 v[4:5], v[4:5], 1.0 op_sel_hi:[1,0]
	s_waitcnt vmcnt(4)
	v_pk_mul_f32 v[10:11], v[10:11], v[14:15]
	v_pk_mul_f32 v[8:9], v[8:9], v[12:13]
	s_waitcnt vmcnt(3)
	v_pk_add_f32 v[12:13], v[18:19], 1.0 op_sel_hi:[1,0]
	v_pk_add_f32 v[14:15], v[16:17], 1.0 op_sel_hi:[1,0]
	s_waitcnt vmcnt(2)
	v_pk_mul_f32 v[2:3], v[2:3], v[22:23]
	v_pk_mul_f32 v[0:1], v[0:1], v[20:21]
	s_waitcnt vmcnt(1)
	v_pk_fma_f32 v[6:7], v[6:7], v[10:11], v[38:39]
	v_pk_fma_f32 v[4:5], v[4:5], v[8:9], v[36:37]
	s_waitcnt vmcnt(0)
	v_pk_fma_f32 v[8:9], v[12:13], v[2:3], v[42:43]
	v_pk_fma_f32 v[2:3], v[14:15], v[0:1], v[40:41]
	v_cvt_pk_bf16_f32 v0, v4, v5
	v_cvt_pk_bf16_f32 v1, v6, v7
	v_cvt_pk_bf16_f32 v2, v2, v3
	v_cvt_pk_bf16_f32 v3, v8, v9
	global_store_dwordx4 v[56:57], v[0:3], off offset:1024
	s_branch .LBB0_677
